# retention: V fragment reads prefetched during the QK tail; next-tile LDS-DMA issued after QK instead of at loop top
# speedup vs baseline: 1.0054x; 1.0054x over previous
.Lt_skipdma:
	s_lshl_b32 s4, s45, 14
	s_add_i32 s4, s4, 0x100000
	v_readlane_b32 s5, v254, 60
	s_lshl_b32 s5, s5, 10
	s_cmp_eq_u32 s49, 0
	s_cselect_b32 m0, 0x8400, 0
	s_add_i32 m0, m0, s5
	v_add_u32_e32 v0, s4, v106
	v_add_u32_e32 v4, s4, v107
	global_load_lds_dwordx4 v0, s[24:25]
	s_add_i32 m0, m0, 0x2000
	s_add_i32 s4, s4, 0x40000
	v_add_u32_e32 v1, s4, v106
	v_add_u32_e32 v5, s4, v107
	global_load_lds_dwordx4 v1, s[24:25]
	s_add_i32 m0, m0, 0x2000
	s_add_i32 s4, s4, 0x40000
	v_add_u32_e32 v2, s4, v106
	v_add_u32_e32 v6, s4, v107
	global_load_lds_dwordx4 v2, s[24:25]
	s_add_i32 m0, m0, 0x2000
	s_add_i32 s4, s4, 0x40000
	v_add_u32_e32 v3, s4, v106
	v_add_u32_e32 v7, s4, v107
	global_load_lds_dwordx4 v3, s[24:25]
	s_cmp_eq_u32 s49, 0
	s_cselect_b32 m0, 0x8800, 0
	s_add_i32 m0, m0, s5
	s_add_i32 m0, m0, 0x10800
	s_nop 0
	global_load_lds_dwordx4 v4, s[26:27]
	s_add_i32 m0, m0, 0x2000
	s_nop 0
	global_load_lds_dwordx4 v5, s[26:27]
	s_add_i32 m0, m0, 0x2000
	s_nop 0
	global_load_lds_dwordx4 v6, s[26:27]
	s_add_i32 m0, m0, 0x2000
	s_nop 0
	global_load_lds_dwordx4 v7, s[26:27]
	s_branch .LBB0_864
.LBB0_863:
	v_cvt_pk_bf16_f32 v6, v174, v175
	v_cvt_pk_bf16_f32 v7, v176, v177
	s_nop 1
	s_waitcnt lgkmcnt(12)
	v_mfma_f32_16x16x32_bf16 v[70:73], v[116:119], v[0:3], v[70:73]
	ds_read_b64_tr_b16 v[116:117], v114
	ds_read_b64_tr_b16 v[118:119], v114 offset:8192
	s_waitcnt lgkmcnt(12)
	v_mfma_f32_16x16x32_bf16 v[66:69], v[120:123], v[0:3], v[66:69]
	ds_read_b64_tr_b16 v[120:121], v115 offset:256
	ds_read_b64_tr_b16 v[122:123], v115 offset:8448
	s_waitcnt lgkmcnt(12)
	v_mfma_f32_16x16x32_bf16 v[62:65], v[124:127], v[0:3], v[62:65]
	ds_read_b64_tr_b16 v[124:125], v108 offset:256
	ds_read_b64_tr_b16 v[126:127], v108 offset:8448
	s_waitcnt lgkmcnt(12)
	v_mfma_f32_16x16x32_bf16 v[58:61], v[128:131], v[0:3], v[58:61]
	ds_read_b64_tr_b16 v[128:129], v109 offset:256
	ds_read_b64_tr_b16 v[130:131], v109 offset:8448
	s_waitcnt lgkmcnt(12)
	v_mfma_f32_16x16x32_bf16 v[54:57], v[210:213], v[0:3], v[54:57]
	ds_read_b64_tr_b16 v[210:211], v110 offset:256
	ds_read_b64_tr_b16 v[212:213], v110 offset:8448
	s_waitcnt lgkmcnt(12)
	v_mfma_f32_16x16x32_bf16 v[50:53], v[202:205], v[0:3], v[50:53]
	ds_read_b64_tr_b16 v[202:203], v111 offset:256
	ds_read_b64_tr_b16 v[204:205], v111 offset:8448
	s_waitcnt lgkmcnt(12)
	v_mfma_f32_16x16x32_bf16 v[46:49], v[206:209], v[0:3], v[46:49]
	ds_read_b64_tr_b16 v[206:207], v112 offset:256
	ds_read_b64_tr_b16 v[208:209], v112 offset:8448
	s_waitcnt lgkmcnt(12)
	v_mfma_f32_16x16x32_bf16 v[42:45], v[116:119], v[0:3], v[42:45]
	ds_read_b64_tr_b16 v[116:117], v113 offset:256
	ds_read_b64_tr_b16 v[118:119], v113 offset:8448
	s_waitcnt lgkmcnt(12)
	v_mfma_f32_16x16x32_bf16 v[38:41], v[120:123], v[0:3], v[38:41]
	ds_read_b64_tr_b16 v[120:121], v114 offset:256
	ds_read_b64_tr_b16 v[122:123], v114 offset:8448
	s_waitcnt lgkmcnt(12)
	v_mfma_f32_16x16x32_bf16 v[34:37], v[124:127], v[0:3], v[34:37]
	ds_read_b64_tr_b16 v[124:125], v115 offset:16384
	ds_read_b64_tr_b16 v[126:127], v115 offset:24576
	s_waitcnt lgkmcnt(12)
	v_mfma_f32_16x16x32_bf16 v[30:33], v[128:131], v[0:3], v[30:33]
	ds_read_b64_tr_b16 v[128:129], v108 offset:16384
	ds_read_b64_tr_b16 v[130:131], v108 offset:24576
	s_waitcnt lgkmcnt(12)
	v_mfma_f32_16x16x32_bf16 v[26:29], v[210:213], v[0:3], v[26:29]
	ds_read_b64_tr_b16 v[210:211], v109 offset:16384
	ds_read_b64_tr_b16 v[212:213], v109 offset:24576
	s_waitcnt lgkmcnt(12)
	v_mfma_f32_16x16x32_bf16 v[22:25], v[202:205], v[0:3], v[22:25]
	ds_read_b64_tr_b16 v[202:203], v110 offset:16384
	ds_read_b64_tr_b16 v[204:205], v110 offset:24576
	s_waitcnt lgkmcnt(12)
	v_mfma_f32_16x16x32_bf16 v[18:21], v[206:209], v[0:3], v[18:21]
	ds_read_b64_tr_b16 v[206:207], v111 offset:16384
	ds_read_b64_tr_b16 v[208:209], v111 offset:24576
	s_waitcnt lgkmcnt(12)
	v_mfma_f32_16x16x32_bf16 v[14:17], v[116:119], v[0:3], v[14:17]
	ds_read_b64_tr_b16 v[116:117], v112 offset:16384
	ds_read_b64_tr_b16 v[118:119], v112 offset:24576
	s_waitcnt lgkmcnt(12)
	v_mfma_f32_16x16x32_bf16 v[10:13], v[120:123], v[0:3], v[10:13]
	ds_read_b64_tr_b16 v[120:121], v113 offset:16384
	ds_read_b64_tr_b16 v[122:123], v113 offset:24576
	s_waitcnt lgkmcnt(12)
	v_mfma_f32_16x16x32_bf16 v[70:73], v[124:127], v[4:7], v[70:73]
	ds_read_b64_tr_b16 v[124:125], v114 offset:16384
	ds_read_b64_tr_b16 v[126:127], v114 offset:24576
	s_waitcnt lgkmcnt(12)
	v_mfma_f32_16x16x32_bf16 v[66:69], v[128:131], v[4:7], v[66:69]
	ds_read_b64_tr_b16 v[128:129], v115 offset:16640
	ds_read_b64_tr_b16 v[130:131], v115 offset:24832
	s_waitcnt lgkmcnt(12)
	v_mfma_f32_16x16x32_bf16 v[62:65], v[210:213], v[4:7], v[62:65]
	ds_read_b64_tr_b16 v[210:211], v108 offset:16640
	ds_read_b64_tr_b16 v[212:213], v108 offset:24832
	s_waitcnt lgkmcnt(12)
	v_mfma_f32_16x16x32_bf16 v[58:61], v[202:205], v[4:7], v[58:61]
	ds_read_b64_tr_b16 v[202:203], v109 offset:16640
	ds_read_b64_tr_b16 v[204:205], v109 offset:24832
	s_waitcnt lgkmcnt(12)
	v_mfma_f32_16x16x32_bf16 v[54:57], v[206:209], v[4:7], v[54:57]
	ds_read_b64_tr_b16 v[206:207], v110 offset:16640
	ds_read_b64_tr_b16 v[208:209], v110 offset:24832
	s_waitcnt lgkmcnt(12)
	v_mfma_f32_16x16x32_bf16 v[50:53], v[116:119], v[4:7], v[50:53]
	ds_read_b64_tr_b16 v[116:117], v111 offset:16640
	ds_read_b64_tr_b16 v[118:119], v111 offset:24832
	s_waitcnt lgkmcnt(12)
	v_mfma_f32_16x16x32_bf16 v[46:49], v[120:123], v[4:7], v[46:49]
	ds_read_b64_tr_b16 v[120:121], v112 offset:16640
	ds_read_b64_tr_b16 v[122:123], v112 offset:24832
	s_waitcnt lgkmcnt(12)
	v_mfma_f32_16x16x32_bf16 v[42:45], v[124:127], v[4:7], v[42:45]
	ds_read_b64_tr_b16 v[124:125], v113 offset:16640
	ds_read_b64_tr_b16 v[126:127], v113 offset:24832
	s_waitcnt lgkmcnt(12)
	v_mfma_f32_16x16x32_bf16 v[38:41], v[128:131], v[4:7], v[38:41]
	ds_read_b64_tr_b16 v[128:129], v114 offset:16640
	ds_read_b64_tr_b16 v[130:131], v114 offset:24832
	s_waitcnt lgkmcnt(12)
	v_mfma_f32_16x16x32_bf16 v[34:37], v[210:213], v[4:7], v[34:37]
	s_waitcnt lgkmcnt(10)
	v_mfma_f32_16x16x32_bf16 v[30:33], v[202:205], v[4:7], v[30:33]
	s_waitcnt lgkmcnt(8)
	v_mfma_f32_16x16x32_bf16 v[26:29], v[206:209], v[4:7], v[26:29]
	s_waitcnt lgkmcnt(6)
	v_mfma_f32_16x16x32_bf16 v[22:25], v[116:119], v[4:7], v[22:25]
	s_waitcnt lgkmcnt(4)
	v_mfma_f32_16x16x32_bf16 v[18:21], v[120:123], v[4:7], v[18:21]
	s_waitcnt lgkmcnt(2)
	v_mfma_f32_16x16x32_bf16 v[14:17], v[124:127], v[4:7], v[14:17]
	s_waitcnt lgkmcnt(0)
	v_mfma_f32_16x16x32_bf16 v[10:13], v[128:131], v[4:7], v[10:13]

.LBB0_865:
	s_and_b32 s49, s48, 1
	s_cmp_gt_i32 s45, s16
	s_cbranch_scc1 .Lt_skipdma
	s_mul_i32 s4, s49, 0x8400
	v_add_u32_e32 v8, s4, v195
	v_xor_b32_e32 v246, 64, v8
	v_xor_b32_e32 v247, 0x80, v8
	v_xor_b32_e32 v248, 0xc0, v8
	ds_read_b128 v[0:3], v8
	ds_read_b128 v[4:7], v8 offset:8192
	ds_read_b128 v[174:177], v8 offset:16384
	ds_read_b128 v[198:201], v8 offset:24576
	ds_read_b128 v[202:205], v246
	ds_read_b128 v[206:209], v246 offset:8192
	ds_read_b128 v[210:213], v246 offset:16384
	ds_read_b128 v[214:217], v246 offset:24576
	ds_read_b128 v[218:221], v247
	ds_read_b128 v[226:229], v247 offset:8192
	ds_read_b128 v[230:233], v247 offset:16384
	ds_read_b128 v[234:237], v247 offset:24576
	ds_read_b128 v[238:241], v248
	ds_read_b128 v[242:245], v248 offset:8192
	s_mul_i32 s5, s49, 0x8800
	v_add_u32_e32 v115, s5, v173
	v_xor_b32_e32 v108, 0x20, v115
	v_xor_b32_e32 v109, 0x40, v115
	v_xor_b32_e32 v110, 0x60, v115
	v_xor_b32_e32 v111, 0x80, v115
	v_xor_b32_e32 v112, 0xa0, v115
	v_xor_b32_e32 v113, 0xc0, v115
	v_xor_b32_e32 v114, 0xe0, v115
	s_add_i32 s4, s45, 63
	s_cmp_le_u32 s4, s9
	s_waitcnt lgkmcnt(13)
	v_mfma_f32_16x16x32_bf16 v[150:153], v[0:3], v[102:105], 0
	ds_read_b128 v[0:3], v248 offset:16384
	s_waitcnt lgkmcnt(13)
	v_mfma_f32_16x16x32_bf16 v[146:149], v[4:7], v[102:105], 0
	ds_read_b128 v[4:7], v248 offset:24576
	s_waitcnt lgkmcnt(13)
	v_mfma_f32_16x16x32_bf16 v[142:145], v[174:177], v[102:105], 0
	ds_read_b128 v[174:177], v8 offset:256
	s_waitcnt lgkmcnt(13)
	v_mfma_f32_16x16x32_bf16 v[138:141], v[198:201], v[102:105], 0
	ds_read_b128 v[198:201], v8 offset:8448
	s_waitcnt lgkmcnt(13)
	v_mfma_f32_16x16x32_bf16 v[150:153], v[202:205], v[98:101], v[150:153]
	ds_read_b128 v[202:205], v8 offset:16640
	s_waitcnt lgkmcnt(13)
	v_mfma_f32_16x16x32_bf16 v[146:149], v[206:209], v[98:101], v[146:149]
	ds_read_b128 v[206:209], v8 offset:24832
	s_waitcnt lgkmcnt(13)
	v_mfma_f32_16x16x32_bf16 v[142:145], v[210:213], v[98:101], v[142:145]
	ds_read_b128 v[210:213], v246 offset:256
	s_waitcnt lgkmcnt(13)
	v_mfma_f32_16x16x32_bf16 v[138:141], v[214:217], v[98:101], v[138:141]
	ds_read_b128 v[214:217], v246 offset:8448
	s_waitcnt lgkmcnt(13)
	v_mfma_f32_16x16x32_bf16 v[150:153], v[218:221], v[94:97], v[150:153]
	ds_read_b128 v[218:221], v246 offset:16640
	s_waitcnt lgkmcnt(13)
	v_mfma_f32_16x16x32_bf16 v[146:149], v[226:229], v[94:97], v[146:149]
	ds_read_b128 v[226:229], v246 offset:24832
	s_waitcnt lgkmcnt(13)
	v_mfma_f32_16x16x32_bf16 v[142:145], v[230:233], v[94:97], v[142:145]
	ds_read_b128 v[230:233], v247 offset:256
	s_waitcnt lgkmcnt(13)
	v_mfma_f32_16x16x32_bf16 v[138:141], v[234:237], v[94:97], v[138:141]
	ds_read_b128 v[234:237], v247 offset:8448
	s_waitcnt lgkmcnt(13)
	v_mfma_f32_16x16x32_bf16 v[150:153], v[238:241], v[90:93], v[150:153]
	ds_read_b128 v[238:241], v247 offset:16640
	s_waitcnt lgkmcnt(13)
	v_mfma_f32_16x16x32_bf16 v[146:149], v[242:245], v[90:93], v[146:149]
	ds_read_b128 v[242:245], v247 offset:24832
	s_waitcnt lgkmcnt(13)
	v_mfma_f32_16x16x32_bf16 v[142:145], v[0:3], v[90:93], v[142:145]
	ds_read_b128 v[0:3], v248 offset:256
	s_waitcnt lgkmcnt(13)
	v_mfma_f32_16x16x32_bf16 v[138:141], v[4:7], v[90:93], v[138:141]
	ds_read_b128 v[4:7], v248 offset:8448
	s_waitcnt lgkmcnt(13)
	v_mfma_f32_16x16x32_bf16 v[150:153], v[174:177], v[86:89], v[150:153]
	ds_read_b128 v[174:177], v248 offset:16640
	s_waitcnt lgkmcnt(13)
	v_mfma_f32_16x16x32_bf16 v[146:149], v[198:201], v[86:89], v[146:149]
	ds_read_b128 v[198:201], v248 offset:24832
	s_waitcnt lgkmcnt(13)
	v_mfma_f32_16x16x32_bf16 v[142:145], v[202:205], v[86:89], v[142:145]
	ds_read_b64_tr_b16 v[116:117], v115
	ds_read_b64_tr_b16 v[118:119], v115 offset:8192
	s_waitcnt lgkmcnt(14)
	v_mfma_f32_16x16x32_bf16 v[138:141], v[206:209], v[86:89], v[138:141]
	ds_read_b64_tr_b16 v[120:121], v108
	s_waitcnt lgkmcnt(14)
	v_mfma_f32_16x16x32_bf16 v[150:153], v[210:213], v[82:85], v[150:153]
	ds_read_b64_tr_b16 v[122:123], v108 offset:8192
	s_waitcnt lgkmcnt(14)
	v_mfma_f32_16x16x32_bf16 v[146:149], v[214:217], v[82:85], v[146:149]
	ds_read_b64_tr_b16 v[124:125], v109
	s_waitcnt lgkmcnt(14)
	v_mfma_f32_16x16x32_bf16 v[142:145], v[218:221], v[82:85], v[142:145]
	ds_read_b64_tr_b16 v[126:127], v109 offset:8192
	s_waitcnt lgkmcnt(14)
	v_mfma_f32_16x16x32_bf16 v[138:141], v[226:229], v[82:85], v[138:141]
	ds_read_b64_tr_b16 v[128:129], v110
	s_waitcnt lgkmcnt(14)
	v_mfma_f32_16x16x32_bf16 v[150:153], v[230:233], v[78:81], v[150:153]
	ds_read_b64_tr_b16 v[130:131], v110 offset:8192
	s_waitcnt lgkmcnt(14)
	v_mfma_f32_16x16x32_bf16 v[146:149], v[234:237], v[78:81], v[146:149]
	ds_read_b64_tr_b16 v[210:211], v111
	s_waitcnt lgkmcnt(14)
	v_mfma_f32_16x16x32_bf16 v[142:145], v[238:241], v[78:81], v[142:145]
	ds_read_b64_tr_b16 v[212:213], v111 offset:8192
	s_waitcnt lgkmcnt(14)
	v_mfma_f32_16x16x32_bf16 v[138:141], v[242:245], v[78:81], v[138:141]
	ds_read_b64_tr_b16 v[202:203], v112
	s_waitcnt lgkmcnt(14)
	v_mfma_f32_16x16x32_bf16 v[150:153], v[0:3], v[74:77], v[150:153]
	ds_read_b64_tr_b16 v[204:205], v112 offset:8192
	s_waitcnt lgkmcnt(14)
	v_mfma_f32_16x16x32_bf16 v[146:149], v[4:7], v[74:77], v[146:149]
	ds_read_b64_tr_b16 v[206:207], v113
	s_waitcnt lgkmcnt(14)
	v_mfma_f32_16x16x32_bf16 v[142:145], v[174:177], v[74:77], v[142:145]
	ds_read_b64_tr_b16 v[208:209], v113 offset:8192
	s_waitcnt lgkmcnt(14)
	v_mfma_f32_16x16x32_bf16 v[138:141], v[198:201], v[74:77], v[138:141]
	s_lshl_b32 s4, s45, 14
	s_add_i32 s4, s4, 0x100000
	v_readlane_b32 s5, v254, 60
	s_lshl_b32 s5, s5, 10
	s_cmp_eq_u32 s49, 0
	s_cselect_b32 m0, 0x8400, 0
	s_add_i32 m0, m0, s5
	v_add_u32_e32 v0, s4, v106
	v_add_u32_e32 v4, s4, v107
	global_load_lds_dwordx4 v0, s[24:25]
	s_add_i32 m0, m0, 0x2000
	s_add_i32 s4, s4, 0x40000
	v_add_u32_e32 v1, s4, v106
	v_add_u32_e32 v5, s4, v107
	global_load_lds_dwordx4 v1, s[24:25]
	s_add_i32 m0, m0, 0x2000
	s_add_i32 s4, s4, 0x40000
	v_add_u32_e32 v2, s4, v106
	v_add_u32_e32 v6, s4, v107
	global_load_lds_dwordx4 v2, s[24:25]
	s_add_i32 m0, m0, 0x2000
	s_add_i32 s4, s4, 0x40000
	v_add_u32_e32 v3, s4, v106
	v_add_u32_e32 v7, s4, v107
	global_load_lds_dwordx4 v3, s[24:25]
	s_cmp_eq_u32 s49, 0
	s_cselect_b32 m0, 0x8800, 0
	s_add_i32 m0, m0, s5
	s_add_i32 m0, m0, 0x10800
	s_nop 0
	global_load_lds_dwordx4 v4, s[26:27]
	s_add_i32 m0, m0, 0x2000
	s_nop 0
	global_load_lds_dwordx4 v5, s[26:27]
	s_add_i32 m0, m0, 0x2000
	s_nop 0
	global_load_lds_dwordx4 v6, s[26:27]
	s_add_i32 m0, m0, 0x2000
	s_nop 0
	global_load_lds_dwordx4 v7, s[26:27]
	s_add_i32 s4, s45, 63
	s_cmp_le_u32 s4, s9
	s_mov_b64 s[4:5], -1
	s_cbranch_scc0 .LBB0_868
	v_cvt_f32_i32_e32 v0, v196
	s_mov_b64 s[4:5], 0
	v_mul_f32_e32 v0, v178, v0
	v_exp_f32_e32 v8, v0
	s_nop 0
	v_mul_f32_e32 v0, s40, v8
	v_pk_mul_f32 v[2:3], s[40:41], v[0:1] op_sel_hi:[1,0]
	v_pk_mul_f32 v[0:1], s[42:43], v[0:1] op_sel_hi:[1,0]
	v_pk_mul_f32 v[2:3], v[2:3], v[150:151]
	v_pk_mul_f32 v[4:5], v[0:1], v[152:153]
	v_cvt_pk_bf16_f32 v0, v2, v3
	v_mul_f32_e32 v2, s44, v8
	v_cvt_pk_bf16_f32 v1, v4, v5
	v_pk_mul_f32 v[4:5], s[40:41], v[2:3] op_sel_hi:[1,0]
	v_pk_mul_f32 v[2:3], s[42:43], v[2:3] op_sel_hi:[1,0]
	v_pk_mul_f32 v[4:5], v[4:5], v[146:147]
	v_pk_mul_f32 v[6:7], v[2:3], v[148:149]
	v_cvt_pk_bf16_f32 v2, v4, v5
	v_mul_f32_e32 v4, s37, v8
	v_cvt_pk_bf16_f32 v3, v6, v7
	v_pk_mul_f32 v[6:7], s[40:41], v[4:5] op_sel_hi:[1,0]
	v_pk_mul_f32 v[4:5], s[42:43], v[4:5] op_sel_hi:[1,0]
	v_pk_mul_f32 v[6:7], v[6:7], v[142:143]
	v_pk_mul_f32 v[154:155], v[4:5], v[144:145]
	v_cvt_pk_bf16_f32 v4, v6, v7
	v_mul_f32_e32 v6, s36, v8
	v_cvt_pk_bf16_f32 v5, v154, v155
	v_pk_mul_f32 v[154:155], s[40:41], v[6:7] op_sel_hi:[1,0]
	v_pk_mul_f32 v[6:7], s[42:43], v[6:7] op_sel_hi:[1,0]
	v_pk_mul_f32 v[174:175], v[154:155], v[138:139]
	v_pk_mul_f32 v[176:177], v[6:7], v[140:141]
